# v43: grid barrier direct release - the last XCD leader bumps all per-XCD generation words itself; other leaders spin on their XCD word; no per-leader bump (v41 + barrier change)
# baseline (speedup 1.0000x reference)
.LBB0_254:
	s_or_b64 exec, exec, s[6:7]
	s_waitcnt vmcnt(0)
	v_readfirstlane_b32 s4, v2
	v_cvt_f32_u32_e32 v2, v0
	v_sub_u32_e32 v3, 0, v0
	v_add_u32_e32 v1, s4, v1
	v_readlane_b32 s4, v254, 37
	v_rcp_iflag_f32_e32 v2, v2
	v_readlane_b32 s5, v254, 38
	s_mov_b64 s[6:7], -1
	v_mul_f32_e32 v2, 0x4f7ffffe, v2
	v_cvt_u32_f32_e32 v2, v2
	v_mul_lo_u32 v3, v3, v2
	v_mul_hi_u32 v3, v2, v3
	v_add_u32_e32 v2, v2, v3
	v_mul_hi_u32 v2, v1, v2
	v_mul_lo_u32 v3, v2, v0
	v_sub_u32_e32 v3, v1, v3
	v_cmp_ge_u32_e32 vcc, v3, v0
	v_add_u32_e32 v4, 1, v2
	v_add_u32_e32 v1, 1, v1
	v_cndmask_b32_e32 v2, v2, v4, vcc
	v_sub_u32_e32 v4, v3, v0
	v_cndmask_b32_e32 v3, v3, v4, vcc
	v_cmp_ge_u32_e32 vcc, v3, v0
	v_add_u32_e32 v3, 1, v2
	s_nop 0
	v_cndmask_b32_e32 v2, v2, v3, vcc
	v_mul_lo_u32 v3, v0, v2
	v_add_u32_e32 v0, v3, v0
	v_cmp_ne_u32_e32 vcc, v1, v0
	v_mov_b64_e32 v[0:1], s[4:5]
	s_cbranch_vccnz .Lxb_nl_0
	v_readlane_b32 s12, v254, 35
	v_readlane_b32 s13, v254, 36
	s_nop 0
	s_sub_u32 s12, s12, 0x1000
	s_subb_u32 s13, s13, 0
	global_atomic_add v201, v239, s[12:13]
	s_add_u32 s12, s12, 0x100
	s_addc_u32 s13, s13, 0
	global_atomic_add v201, v239, s[12:13]
	s_add_u32 s12, s12, 0x100
	s_addc_u32 s13, s13, 0
	global_atomic_add v201, v239, s[12:13]
	s_add_u32 s12, s12, 0x100
	s_addc_u32 s13, s13, 0
	global_atomic_add v201, v239, s[12:13]
	s_add_u32 s12, s12, 0x100
	s_addc_u32 s13, s13, 0
	global_atomic_add v201, v239, s[12:13]
	s_add_u32 s12, s12, 0x100
	s_addc_u32 s13, s13, 0
	global_atomic_add v201, v239, s[12:13]
	s_add_u32 s12, s12, 0x100
	s_addc_u32 s13, s13, 0
	global_atomic_add v201, v239, s[12:13]
	s_add_u32 s12, s12, 0x100
	s_addc_u32 s13, s13, 0
	global_atomic_add v201, v239, s[12:13]
	s_add_u32 s12, s12, 0x100
	s_addc_u32 s13, s13, 0
	global_atomic_add v201, v239, s[12:13]
	s_add_u32 s12, s12, 0x100
	s_addc_u32 s13, s13, 0
	global_atomic_add v201, v239, s[12:13]
	s_add_u32 s12, s12, 0x100
	s_addc_u32 s13, s13, 0
	global_atomic_add v201, v239, s[12:13]
	s_add_u32 s12, s12, 0x100
	s_addc_u32 s13, s13, 0
	global_atomic_add v201, v239, s[12:13]
	s_add_u32 s12, s12, 0x100
	s_addc_u32 s13, s13, 0
	global_atomic_add v201, v239, s[12:13]
	s_add_u32 s12, s12, 0x100
	s_addc_u32 s13, s13, 0
	global_atomic_add v201, v239, s[12:13]
	s_add_u32 s12, s12, 0x100
	s_addc_u32 s13, s13, 0
	global_atomic_add v201, v239, s[12:13]
	s_add_u32 s12, s12, 0x100
	s_addc_u32 s13, s13, 0
	global_atomic_add v201, v239, s[12:13]
.Lxb_nl_0:
	s_and_saveexec_b64 s[4:5], vcc
	s_cbranch_execz .LBB0_266
	v_readlane_b32 s6, v254, 33
	v_readlane_b32 s7, v254, 34
	s_mov_b64 s[34:35], 0
	s_nop 3
	global_load_dword v0, v201, s[6:7] sc1
	s_waitcnt vmcnt(0)
	v_cmp_eq_u32_e32 vcc, v0, v2
	s_and_saveexec_b64 s[6:7], vcc
	s_cbranch_execz .LBB0_265
	s_mov_b32 s14, 1
	s_branch .LBB0_258

.LBB0_262:
	v_readlane_b32 s12, v254, 33
	v_readlane_b32 s13, v254, 34
	s_add_i32 s14, s14, 1
	s_mov_b64 s[42:43], -1
	s_nop 2
	global_load_dword v0, v201, s[12:13] sc1
	s_waitcnt vmcnt(0)
	v_cmp_ne_u32_e32 vcc, v0, v2
	s_orn2_b64 s[40:41], vcc, exec
	s_branch .LBB0_257

.LBB0_268:
	s_or_b64 exec, exec, s[4:5]
	s_mov_b64 s[4:5], exec
	v_mbcnt_lo_u32_b32 v0, s4, 0
	v_mbcnt_hi_u32_b32 v0, s5, v0
	v_cmp_eq_u32_e32 vcc, 0, v0
	s_waitcnt vmcnt(0)
	buffer_inv sc1
	s_and_saveexec_b64 s[6:7], vcc
	s_cbranch_execz .LBB0_270
	s_bcnt1_i32_b64 s4, s[4:5]
	v_mov_b32_e32 v0, s4
	v_readlane_b32 s4, v254, 33
	v_readlane_b32 s5, v254, 34
	s_nop 4
	s_nop 0

.Lxb_nl_2:
	s_and_saveexec_b64 s[4:5], vcc
	s_cbranch_execz .LBB0_514
	v_readlane_b32 s6, v254, 33
	v_readlane_b32 s7, v254, 34
	s_mov_b64 s[34:35], 0
	s_nop 3
	global_load_dword v0, v201, s[6:7] sc1
	s_waitcnt vmcnt(0)
	v_cmp_eq_u32_e32 vcc, v0, v2
	s_and_saveexec_b64 s[6:7], vcc
	s_cbranch_execz .LBB0_513
	s_mov_b32 s16, 1
	s_branch .LBB0_506

.LBB0_510:
	v_readlane_b32 s12, v254, 33
	v_readlane_b32 s13, v254, 34
	s_add_i32 s16, s16, 1
	s_mov_b64 s[42:43], -1
	s_nop 2
	global_load_dword v0, v201, s[12:13] sc1
	s_waitcnt vmcnt(0)
	v_cmp_ne_u32_e32 vcc, v0, v2
	s_orn2_b64 s[40:41], vcc, exec
	s_branch .LBB0_505

.LBB0_842:
	v_readlane_b32 s12, v254, 33
	v_readlane_b32 s13, v254, 34
	s_add_i32 s14, s14, 1
	s_mov_b64 s[50:51], -1
	s_nop 2
	global_load_dword v0, v201, s[12:13] sc1
	s_waitcnt vmcnt(0)
	v_cmp_ne_u32_e32 vcc, v0, v2
	s_orn2_b64 s[44:45], vcc, exec
	s_branch .LBB0_837

.LBB0_1107:
	s_bcnt1_i32_b64 s4, s[4:5]
	v_mov_b32_e32 v0, s4
	v_readlane_b32 s4, v254, 33
	v_readlane_b32 s5, v254, 34
	s_nop 4
	s_nop 0
	s_getpc_b64 s[98:99]
